# m23 + attention loops shifted 56 bytes by unreachable padding (instruction-fetch phase)
# baseline (speedup 1.0000x reference)
; __device__ __forceinline__ float wave_sum(float v) {
; #pragma unroll
;     for (int o = 1; o < 64; o <<= 1) v += __shfl_xor(v, o);
;     return v;
; __global__ void __launch_bounds__(512, 2) mk_fwd(Args a) {
;     ...
;                 int ll = lane; asm volatile("" : "+v"(ll));
;                 const float s1 = wave_sum(a.in[10][ll] * a.in[11][ll]), s2 = wave_sum(a.in[12][ll] * a.in[13][ll]);
;                 const float lam = __expf(s1) - __expf(s2) + 0.2f;
.LBB0_494:
	v_readlane_b32 s4, v254, 33
	v_readlane_b32 s5, v254, 34
	s_andn2_b64 vcc, exec, s[4:5]
	s_cbranch_vccnz .LBB0_611
	s_load_dwordx8 s[12:19], s[0:1], 0x50
	v_mov_b32_e32 v144, v203
	v_xor_b32_e32 v6, 2, v211
	v_ashrrev_i32_e32 v145, 31, v144
	s_waitcnt lgkmcnt(0)
	v_lshlrev_b64 v[0:1], 2, v[144:145]
	v_lshl_add_u64 v[2:3], s[12:13], 0, v[0:1]
	global_load_dword v4, v[2:3], off
	v_lshl_add_u64 v[2:3], s[14:15], 0, v[0:1]
	global_load_dword v5, v[2:3], off
	v_lshl_add_u64 v[2:3], s[16:17], 0, v[0:1]
	v_lshl_add_u64 v[0:1], s[18:19], 0, v[0:1]
	global_load_dword v2, v[2:3], off
	v_xor_b32_e32 v3, 1, v211
	global_load_dword v0, v[0:1], off
	v_and_b32_e32 v1, 64, v211
	v_add_u32_e32 v1, 64, v1
	v_cmp_lt_i32_e32 vcc, v3, v1
	v_xor_b32_e32 v7, 4, v211
	v_xor_b32_e32 v8, 8, v211
	v_cndmask_b32_e32 v3, v211, v3, vcc
	v_lshlrev_b32_e32 v3, 2, v3
	v_cmp_lt_i32_e32 vcc, v6, v1
	v_xor_b32_e32 v9, 16, v211
	v_xor_b32_e32 v10, 32, v211
	v_cndmask_b32_e32 v6, v211, v6, vcc
	v_lshlrev_b32_e32 v6, 2, v6
	v_cmp_lt_i32_e32 vcc, v7, v1
	s_mov_b32 s4, 0
	s_waitcnt vmcnt(2)
	v_mul_f32_e32 v11, v4, v5
	ds_bpermute_b32 v11, v3, v11
	s_waitcnt vmcnt(0)
	v_mul_f32_e32 v12, v2, v0
	ds_bpermute_b32 v3, v3, v12
	s_waitcnt lgkmcnt(1)
	v_fmac_f32_e32 v11, v4, v5
	v_cndmask_b32_e32 v4, v211, v7, vcc
	v_lshlrev_b32_e32 v4, 2, v4
	v_cmp_lt_i32_e32 vcc, v8, v1
	s_waitcnt lgkmcnt(0)
	v_fmac_f32_e32 v3, v2, v0
	ds_bpermute_b32 v0, v6, v11
	ds_bpermute_b32 v2, v6, v3
	v_cndmask_b32_e32 v5, v211, v8, vcc
	v_lshlrev_b32_e32 v5, 2, v5
	v_cmp_lt_i32_e32 vcc, v9, v1
	s_waitcnt lgkmcnt(1)
	v_add_f32_e32 v0, v11, v0
	s_waitcnt lgkmcnt(0)
	v_add_f32_e32 v2, v3, v2
	ds_bpermute_b32 v3, v4, v0
	ds_bpermute_b32 v4, v4, v2
	s_waitcnt lgkmcnt(1)
	v_add_f32_e32 v0, v0, v3
	s_waitcnt lgkmcnt(0)
	v_add_f32_e32 v2, v2, v4
	ds_bpermute_b32 v3, v5, v0
	ds_bpermute_b32 v4, v5, v2
	v_cndmask_b32_e32 v5, v211, v9, vcc
	v_lshlrev_b32_e32 v5, 2, v5
	v_cmp_lt_i32_e32 vcc, v10, v1
	s_waitcnt lgkmcnt(1)
	v_add_f32_e32 v0, v0, v3
	s_waitcnt lgkmcnt(0)
	v_add_f32_e32 v2, v2, v4
	ds_bpermute_b32 v3, v5, v0
	ds_bpermute_b32 v4, v5, v2
	v_cndmask_b32_e32 v1, v211, v10, vcc
	v_lshlrev_b32_e32 v145, 2, v1
	s_waitcnt lgkmcnt(1)
	v_add_f32_e32 v0, v0, v3
	s_waitcnt lgkmcnt(0)
	v_add_f32_e32 v1, v2, v4
	ds_bpermute_b32 v2, v145, v0
	ds_bpermute_b32 v3, v145, v1
	s_waitcnt lgkmcnt(1)
	v_add_f32_e32 v0, v0, v2
	s_waitcnt lgkmcnt(0)
	v_add_f32_e32 v1, v1, v3
	v_mul_f32_e32 v0, 0x3fb8aa3b, v0
	v_mul_f32_e32 v1, 0x3fb8aa3b, v1
	v_exp_f32_e32 v0, v0
	v_exp_f32_e32 v1, v1
	s_nop 0
	v_sub_f32_e32 v0, v0, v1
	v_add_f32_e32 v154, 0x3e4ccccd, v0
	s_branch .LBB0_497
	s_nop 0
	s_nop 0
	s_nop 0
	s_nop 0
	s_nop 0
	s_nop 0
	s_nop 0
	s_nop 0
	s_nop 0
	s_nop 0
	s_nop 0
	s_nop 0
	s_nop 0
	s_nop 0
